# adds DA wave-half stagger of K/V staging (waves 4-7 defer next-tile staging until after QK MFMAs)
# speedup vs baseline: 1.0163x; 1.0043x over previous
; DI f32x16 zero16() { f32x16 z; for (int i = 0; i < 16; ++i) z[i] = 0.f; return z; }
; DI void phase_da_attn(const Params& p, int j, char* lds) {
;     ...
;     const int qb = kr == 0 ? 15 - g : kr == 1 ? 8 + g : kr == 2 ? 7 - g : g;
;     const int b = bh & 7, h = bh >> 3;
;     const int q0 = qb * 128 + qg * 32;
;     const int myq = q0 + l31;
;     const size_t tokb = (size_t)b * S_;
;     bf16x8 qf[4];
; #pragma unroll
;     for (int kk = 0; kk < 4; ++kk) qf[kk] = *(const bf16x8*)(Q + (tokb + myq) * D_ + h * 128 + c * 64 + kk * 16 + 8 * hh);
;     f32x16 o[4];
; #pragma unroll
;     for (int et = 0; et < 4; ++et) o[et] = zero16();
;     float m = -1e30f, l = 0.f;
;     const int nkt = 2 * (qb + 1);
;     u32x4 rk[2], rv[2];
;     auto gload = [&](int kt) {
; #pragma unroll
;       for (int i = 0; i < 2; ++i) {
;         int idx = tid + i * NT;
;         { int row = idx >> 4, ch = idx & 15; rk[i] = *(const u32x4*)(K + (tokb + kt * 64 + row) * D_ + h * 128 + ch * 8); }
;         { int row = idx >> 3, ch = idx & 7; rv[i] = *(const u32x4*)(Vt + ((size_t)(b * 8 + h) * 128 + row) * S_ + kt * 64 + ch * 8); }
;       }
;     };
;     auto lwrite = [&](int buf) {
;       char* kt_w = lds + buf * KVB; char* vt_w = kt_w + 16384;
; #pragma unroll
;       for (int i = 0; i < 2; ++i) {
;         int idx = tid + i * NT;
;         { int row = idx >> 4, ch = idx & 15; *(u32x4*)(kt_w + row * 256 + ((ch ^ (row & 15)) << 4)) = rk[i]; }
;         { int row = idx >> 3, ch = idx & 7; char* d = vt_w + row * 136 + ch * 16; u32x2 a = {rv[i].x, rv[i].y}, bq = {rv[i].z, rv[i].w}; *(u32x2*)d = a; *(u32x2*)(d + 8) = bq; }
;       }
;     };
;     __syncthreads();
;     gload(0); lwrite(0);
;     if (nkt > 1) gload(1);
;     __syncthreads();
;     for (int kt = 0; kt < nkt; ++kt) {
;       if (kt + 1 < nkt) lwrite((kt + 1) & 1);
;       if (kt + 2 < nkt) gload(kt + 2);
.LBB0_494:
	v_lshl_add_u32 v187, s2, 7, v163
	s_and_b32 s3, s34, 7
	v_or_b32_e32 v154, v187, v143
	s_lshl_b32 s92, s3, 11
	v_ashrrev_i32_e32 v155, 31, v154
	v_lshl_add_u64 v[2:3], v[154:155], 0, s[92:93]
	s_bfe_u32 s30, s34, 0x30003
	v_lshlrev_b64 v[152:153], 11, v[2:3]
	v_lshl_add_u64 v[2:3], s[78:79], 0, v[152:153]
	s_lshl_b32 s35, s30, 7
	s_lshl_b32 s6, s30, 8
	s_mov_b32 s7, s93
	s_lshl_b32 s3, s3, 22
	s_lshl_b32 s30, s30, 19
	v_lshl_add_u64 v[2:3], v[2:3], 0, s[6:7]
	s_lshl_b32 s2, s2, 1
	s_or_b32 s3, s30, s3
	v_lshl_add_u64 v[2:3], v[2:3], 0, v[0:1]
	v_mov_b32_e32 v147, v1
	s_add_u32 s30, s82, s3
	v_lshl_add_u64 v[2:3], v[2:3], 0, v[146:147]
	v_lshl_add_u64 v[156:157], s[92:93], 0, v[132:133]
	s_addc_u32 s31, s83, 0
	global_load_dwordx4 v[110:113], v[2:3], off
	global_load_dwordx4 v[106:109], v[2:3], off offset:32
	global_load_dwordx4 v[102:105], v[2:3], off offset:64
	global_load_dwordx4 v[98:101], v[2:3], off offset:96
	v_lshlrev_b64 v[2:3], 11, v[156:157]
	v_lshl_add_u64 v[4:5], s[30:31], 0, v[134:135]
	v_mov_b32_e32 v151, v1
	v_lshl_add_u64 v[160:161], s[92:93], 0, v[136:137]
	v_lshl_add_u64 v[2:3], s[80:81], 0, v[2:3]
	v_lshl_add_u64 v[158:159], v[4:5], 0, v[150:151]
	v_lshlrev_b64 v[4:5], 11, v[160:161]
	v_lshl_add_u64 v[2:3], v[2:3], 0, s[6:7]
	v_mov_b32_e32 v149, v1
	v_lshl_add_u64 v[4:5], s[80:81], 0, v[4:5]
	v_lshl_add_u64 v[2:3], v[2:3], 0, v[148:149]
	v_lshl_add_u64 v[4:5], v[4:5], 0, s[6:7]
	s_mov_b32 s3, 0x20000
	s_barrier
	global_load_dwordx4 v[16:19], v[158:159], off
	v_lshl_add_u64 v[4:5], v[4:5], 0, v[148:149]
	global_load_dwordx4 v[20:23], v[2:3], off
	global_load_dwordx4 v[24:27], v[4:5], off
	v_add_co_u32_e32 v2, vcc, s3, v2
	v_lshl_add_u64 v[6:7], s[30:31], 0, v[138:139]
	s_nop 0
	v_addc_co_u32_e32 v3, vcc, 0, v3, vcc
	v_lshl_add_u64 v[166:167], v[6:7], 0, v[150:151]
	v_add_co_u32_e32 v4, vcc, s3, v4
	global_load_dwordx4 v[28:31], v[166:167], off
	global_load_dwordx4 v[114:117], v[158:159], off offset:128
	v_addc_co_u32_e32 v5, vcc, 0, v5, vcc
	global_load_dwordx4 v[118:121], v[2:3], off
	global_load_dwordx4 v[122:125], v[4:5], off
	global_load_dwordx4 v[126:129], v[166:167], off offset:128
	v_add_u32_e32 v15, v164, v170
	v_add3_u32 v32, v171, v172, s91
	v_add_u32_e32 v33, v173, v174
	v_add3_u32 v34, v175, v172, s91
	v_mov_b32_e32 v2, v1
	v_mov_b32_e32 v3, v1
	v_mov_b32_e32 v4, v1
	v_mov_b32_e32 v5, v1
	v_mov_b32_e32 v6, v1
	v_mov_b32_e32 v7, v1
	v_mov_b32_e32 v8, v1
	v_mov_b32_e32 v9, v1
	v_mov_b32_e32 v10, v1
	v_mov_b32_e32 v11, v1
	v_mov_b32_e32 v12, v1
	v_mov_b32_e32 v13, v1
	v_mov_b32_e32 v14, v1
	s_mov_b32 s44, 0
	v_or_b32_e32 v151, 31, v187
	v_lshl_add_u64 v[168:169], v[140:141], 0, s[6:7]
	s_or_b32 s3, s2, 1
	v_mov_b32_e32 v147, 0
	v_mov_b32_e32 v149, 0xf149f2ca
	s_movk_i32 s6, 0x80
	s_waitcnt vmcnt(6)
	ds_write_b128 v15, v[20:23]
	ds_write2_b64 v32, v[16:17], v[18:19] offset1:1
	s_waitcnt vmcnt(5)
	ds_write_b128 v33, v[24:27]
	s_waitcnt vmcnt(4)
	ds_write2_b64 v34, v[28:29], v[30:31] offset1:1
	v_mov_b32_e32 v16, v1
	v_mov_b32_e32 v17, v1
	v_mov_b32_e32 v15, v1
	v_mov_b64_e32 v[32:33], v[16:17]
	v_mov_b64_e32 v[48:49], v[16:17]
	v_mov_b64_e32 v[64:65], v[16:17]
	v_mov_b64_e32 v[30:31], v[14:15]
	v_mov_b64_e32 v[28:29], v[12:13]
	v_mov_b64_e32 v[26:27], v[10:11]
	v_mov_b64_e32 v[24:25], v[8:9]
	v_mov_b64_e32 v[22:23], v[6:7]
	v_mov_b64_e32 v[20:21], v[4:5]
	v_mov_b64_e32 v[18:19], v[2:3]
	v_mov_b64_e32 v[46:47], v[14:15]
	v_mov_b64_e32 v[44:45], v[12:13]
	v_mov_b64_e32 v[42:43], v[10:11]
	v_mov_b64_e32 v[40:41], v[8:9]
	v_mov_b64_e32 v[38:39], v[6:7]
	v_mov_b64_e32 v[36:37], v[4:5]
	v_mov_b64_e32 v[34:35], v[2:3]
	v_mov_b64_e32 v[62:63], v[14:15]
	v_mov_b64_e32 v[60:61], v[12:13]
	v_mov_b64_e32 v[58:59], v[10:11]
	v_mov_b64_e32 v[56:57], v[8:9]
	v_mov_b64_e32 v[54:55], v[6:7]
	v_mov_b64_e32 v[52:53], v[4:5]
	v_mov_b64_e32 v[50:51], v[2:3]
	v_readfirstlane_b32 s101, v216
	s_lshr_b32 s101, s101, 8
	s_waitcnt lgkmcnt(0)
	s_barrier
.LBB0_495:
	s_add_i32 s37, s44, 1
	s_cmp_eq_u32 s101, 0
	s_cbranch_scc1 .Lda_stage_top
	s_add_i32 s100, s6, 0xffffff80
	v_cmp_le_i32_e32 vcc, s100, v151
	s_cbranch_vccz .Lda_stage_top
	s_add_i32 s100, s6, 0xffffffbf
	v_cmp_gt_i32_e32 vcc, s100, v187
	s_cbranch_vccz .LBB0_497
.Lda_stage_top:
	s_bitcmp1_b32 s37, 0
	s_cselect_b32 s36, 0x8400, 0
	v_add3_u32 v66, s36, v164, v170
	s_waitcnt vmcnt(2)
	ds_write_b128 v66, v[118:121]
	v_add_u32_e32 v66, s36, v171
	v_add3_u32 v66, v66, v172, s91
	ds_write2_b64 v66, v[114:115], v[116:117] offset1:1
	v_add3_u32 v66, s36, v173, v174
	s_waitcnt vmcnt(1)
	ds_write_b128 v66, v[122:125]
	v_add_u32_e32 v66, s36, v175
	v_add3_u32 v66, v66, v172, s91
	s_cmp_ge_u32 s44, s2
	s_waitcnt vmcnt(0)
	ds_write2_b64 v66, v[126:127], v[128:129] offset1:1
	s_cbranch_scc1 .LBB0_497
	s_ashr_i32 s7, s6, 31
	v_lshl_add_u64 v[66:67], v[156:157], 0, s[6:7]
	v_lshlrev_b64 v[66:67], 11, v[66:67]
	v_lshl_add_u64 v[66:67], v[168:169], 0, v[66:67]
	s_lshl_b64 s[30:31], s[6:7], 1
	global_load_dwordx4 v[118:121], v[66:67], off
	v_lshl_add_u64 v[66:67], v[158:159], 0, s[30:31]
	global_load_dwordx4 v[114:117], v[66:67], off
	v_lshl_add_u64 v[66:67], v[160:161], 0, s[6:7]
	v_lshlrev_b64 v[66:67], 11, v[66:67]
	v_lshl_add_u64 v[66:67], v[168:169], 0, v[66:67]
	global_load_dwordx4 v[122:125], v[66:67], off
	v_lshl_add_u64 v[66:67], v[166:167], 0, s[30:31]
	global_load_dwordx4 v[126:129], v[66:67], off
; DI int crow(int i, int hh) { return (i & 3) + 8 * (i >> 2) + 4 * hh; }
; DI f32x16 mfma(bf16x8 a, bf16x8 b, f32x16 c) { return __builtin_amdgcn_mfma_f32_32x32x16_bf16(a, b, c, 0, 0, 0); }
; DI f32x16 zero16() { f32x16 z; for (int i = 0; i < 16; ++i) z[i] = 0.f; return z; }
; DI void phase_da_attn(const Params& p, int j, char* lds) {
;     ...
;       if (kt * 64 <= q0 + 31) {
;         f32x16 st[2];
; #pragma unroll
;         for (int mt = 0; mt < 2; ++mt) {
;           st[mt] = zero16();
;           const int row = mt * 32 + l31;
; #pragma unroll
;           for (int kk = 0; kk < 4; ++kk) {
;             int ch = c * 8 + kk * 2 + hh;
;             bf16x8 a = *(const bf16x8*)(kt_l + row * 256 + ((ch ^ (row & 15)) << 4));
;             st[mt] = mfma(a, qf[kk], st[mt]);
;           }
;         }
;         const bool diag = kt * 64 + 63 > q0;
; #pragma unroll
;         for (int mt = 0; mt < 2; ++mt)
; #pragma unroll
;           for (int i = 0; i < 16; ++i) {
;             float s = st[mt][i] * sc;
;             if (diag) { int key = kt * 64 + mt * 32 + crow(i, hh); if (key > myq) s = -1e30f; }
;             st[mt][i] = s;
;           }
.LBB0_497:
	s_add_i32 s7, s6, 0xffffff80
	v_cmp_le_i32_e32 vcc, s7, v151
	s_and_saveexec_b64 s[30:31], vcc
	s_cbranch_execz .LBB0_501
	s_bitcmp1_b32 s44, 0
	s_cselect_b32 s7, 0x8400, 0
	v_add_u32_e32 v70, s7, v176
	v_add_u32_e32 v71, v70, v182
	s_add_i32 s100, s6, 0xffffffbf
	v_cmp_gt_i32_e32 vcc, s100, v187
	s_cbranch_vccz .Lda_fast
	ds_read_b128 v[66:69], v71
	v_add_u32_e32 v155, v70, v183
	ds_read_b128 v[188:191], v155 offset:8192
	v_add_u32_e32 v192, v70, v184
	v_add_u32_e32 v193, v70, v185
	v_add_u32_e32 v197, s6, v142
	s_add_i32 s44, s6, 0xffffffbf
	v_cmp_gt_i32_e32 vcc, s44, v187
	s_waitcnt lgkmcnt(1)
	v_mfma_f32_32x32x16_bf16 v[82:97], v[66:69], v[110:113], 0
	ds_read_b128 v[66:69], v155
	v_add_u32_e32 v155, 0xffffff80, v197
	v_cmp_gt_i32_e64 s[44:45], v155, v154
	s_and_b64 s[44:45], vcc, s[44:45]
	s_waitcnt lgkmcnt(0)
	v_mfma_f32_32x32x16_bf16 v[82:97], v[66:69], v[106:109], v[82:97]
	ds_read_b128 v[66:69], v192
	s_waitcnt lgkmcnt(0)
	v_mfma_f32_32x32x16_bf16 v[82:97], v[66:69], v[102:105], v[82:97]
	ds_read_b128 v[66:69], v193
	s_waitcnt lgkmcnt(0)
	v_mfma_f32_32x32x16_bf16 v[82:97], v[66:69], v[98:101], v[82:97]
	ds_read_b128 v[66:69], v71 offset:8192
	s_waitcnt lgkmcnt(0)
	v_mfma_f32_32x32x16_bf16 v[66:81], v[66:69], v[110:113], 0
	s_nop 8
	v_mul_f32_e32 v82, 0x3e38aa3b, v82
	v_cndmask_b32_e64 v82, v82, v225, s[44:45]
	v_mul_f32_e32 v83, 0x3e38aa3b, v83
	v_cmp_lt_i32_e64 s[44:45], v155, v154
	v_mul_f32_e32 v84, 0x3e38aa3b, v84
	s_nop 0
	v_cndmask_b32_e64 v155, v225, v83, s[44:45]
	v_mfma_f32_32x32x16_bf16 v[66:81], v[188:191], v[106:109], v[66:81]
	ds_read_b128 v[188:191], v192 offset:8192
	v_cndmask_b32_e32 v83, v83, v155, vcc
	v_add_u32_e32 v155, 0xffffff82, v197
	v_cmp_gt_i32_e64 s[44:45], v155, v154
	s_and_b64 s[44:45], vcc, s[44:45]
	s_nop 0
	v_cndmask_b32_e64 v155, v84, v225, s[44:45]
	s_waitcnt lgkmcnt(0)
	v_mfma_f32_32x32x16_bf16 v[66:81], v[188:191], v[102:105], v[66:81]
	ds_read_b128 v[188:191], v193 offset:8192
	v_mul_f32_e32 v84, 0x3e38aa3b, v85
	v_add_u32_e32 v85, 0xffffff83, v197
	v_cmp_gt_i32_e64 s[44:45], v85, v154
	s_and_b64 s[44:45], vcc, s[44:45]
	v_add_u32_e32 v85, 0xffffff88, v197
	s_waitcnt lgkmcnt(0)
; DI int crow(int i, int hh) { return (i & 3) + 8 * (i >> 2) + 4 * hh; }
; DI void phase_da_attn(const Params& p, int j, char* lds) {
;     ...
;         const bool diag = kt * 64 + 63 > q0;
; #pragma unroll
;         for (int mt = 0; mt < 2; ++mt)
; #pragma unroll
;           for (int i = 0; i < 16; ++i) {
;             float s = st[mt][i] * sc;
;             if (diag) { int key = kt * 64 + mt * 32 + crow(i, hh); if (key > myq) s = -1e30f; }
;             st[mt][i] = s;
;           }
	v_mfma_f32_32x32x16_bf16 v[66:81], v[188:191], v[98:101], v[66:81]
	v_cndmask_b32_e64 v188, v84, v225, s[44:45]
	v_cmp_gt_i32_e64 s[44:45], v85, v154
	v_mul_f32_e32 v84, 0x3e38aa3b, v86
	s_and_b64 s[44:45], vcc, s[44:45]
	v_add_u32_e32 v85, 0xffffff89, v197
	v_cndmask_b32_e64 v193, v84, v225, s[44:45]
	v_cmp_gt_i32_e64 s[44:45], v85, v154
	v_mul_f32_e32 v84, 0x3e38aa3b, v87
	s_and_b64 s[44:45], vcc, s[44:45]
	v_add_u32_e32 v85, 0xffffff8a, v197
	v_cndmask_b32_e64 v194, v84, v225, s[44:45]
	v_cmp_gt_i32_e64 s[44:45], v85, v154
	v_mul_f32_e32 v84, 0x3e38aa3b, v88
	s_and_b64 s[44:45], vcc, s[44:45]
	v_add_u32_e32 v85, 0xffffff8b, v197
	v_cndmask_b32_e64 v195, v84, v225, s[44:45]
	v_cmp_gt_i32_e64 s[44:45], v85, v154
	v_mul_f32_e32 v84, 0x3e38aa3b, v89
	s_and_b64 s[44:45], vcc, s[44:45]
	v_add_u32_e32 v85, 0xffffff90, v197
	v_cndmask_b32_e64 v196, v84, v225, s[44:45]
	v_cmp_gt_i32_e64 s[44:45], v85, v154
	v_mul_f32_e32 v84, 0x3e38aa3b, v90
	s_and_b64 s[44:45], vcc, s[44:45]
	v_add_u32_e32 v85, 0xffffff91, v197
	v_cndmask_b32_e64 v191, v84, v225, s[44:45]
	v_cmp_gt_i32_e64 s[44:45], v85, v154
	v_mul_f32_e32 v84, 0x3e38aa3b, v91
	s_and_b64 s[44:45], vcc, s[44:45]
	v_add_u32_e32 v85, 0xffffff92, v197
	v_cndmask_b32_e64 v192, v84, v225, s[44:45]
	v_cmp_gt_i32_e64 s[44:45], v85, v154
	v_mul_f32_e32 v84, 0x3e38aa3b, v92
	s_and_b64 s[44:45], vcc, s[44:45]
	v_add_u32_e32 v85, 0xffffff93, v197
	v_cndmask_b32_e64 v189, v84, v225, s[44:45]
	v_cmp_gt_i32_e64 s[44:45], v85, v154
	v_mul_f32_e32 v84, 0x3e38aa3b, v93
	s_and_b64 s[44:45], vcc, s[44:45]
	v_add_u32_e32 v85, 0xffffff98, v197
	v_cndmask_b32_e64 v190, v84, v225, s[44:45]
	v_cmp_gt_i32_e64 s[44:45], v85, v154
	v_mul_f32_e32 v84, 0x3e38aa3b, v94
	s_and_b64 s[44:45], vcc, s[44:45]
	v_add_u32_e32 v85, 0xffffff99, v197
	v_cndmask_b32_e64 v93, v84, v225, s[44:45]
	v_cmp_gt_i32_e64 s[44:45], v85, v154
	v_mul_f32_e32 v84, 0x3e38aa3b, v95
	s_and_b64 s[44:45], vcc, s[44:45]
	v_add_u32_e32 v85, 0xffffff9a, v197
	v_cndmask_b32_e64 v94, v84, v225, s[44:45]
	v_cmp_gt_i32_e64 s[44:45], v85, v154
	v_mul_f32_e32 v84, 0x3e38aa3b, v96
	s_and_b64 s[44:45], vcc, s[44:45]
	v_add_u32_e32 v85, 0xffffff9b, v197
	v_cndmask_b32_e64 v95, v84, v225, s[44:45]
	v_cmp_gt_i32_e64 s[44:45], v85, v154
	v_mul_f32_e32 v84, 0x3e38aa3b, v97
	s_and_b64 s[44:45], vcc, s[44:45]
	v_cndmask_b32_e64 v92, v84, v225, s[44:45]
	v_add_u32_e32 v84, 0xffffffa0, v197
	v_cmp_gt_i32_e64 s[44:45], v84, v154
	v_mul_f32_e32 v66, 0x3e38aa3b, v66
	s_and_b64 s[44:45], vcc, s[44:45]
	v_cndmask_b32_e64 v89, v66, v225, s[44:45]
	v_mul_f32_e32 v66, 0x3e38aa3b, v67
	v_add_u32_e32 v67, 0xffffffa1, v197
	v_cmp_gt_i32_e64 s[44:45], v67, v154
	s_and_b64 s[44:45], vcc, s[44:45]
	v_add_u32_e32 v67, 0xffffffa2, v197
	v_cndmask_b32_e64 v85, v66, v225, s[44:45]
	v_cmp_gt_i32_e64 s[44:45], v67, v154
	v_mul_f32_e32 v66, 0x3e38aa3b, v68
	s_and_b64 s[44:45], vcc, s[44:45]
	v_add_u32_e32 v67, 0xffffffa3, v197
	v_cndmask_b32_e64 v87, v66, v225, s[44:45]
	v_cmp_gt_i32_e64 s[44:45], v67, v154
	v_mul_f32_e32 v66, 0x3e38aa3b, v69
	s_and_b64 s[44:45], vcc, s[44:45]
	v_add_u32_e32 v67, 0xffffffa8, v197
	v_cndmask_b32_e64 v90, v66, v225, s[44:45]
	v_cmp_gt_i32_e64 s[44:45], v67, v154
	v_mul_f32_e32 v66, 0x3e38aa3b, v70
	s_and_b64 s[44:45], vcc, s[44:45]
	v_add_u32_e32 v67, 0xffffffa9, v197
	v_cndmask_b32_e64 v86, v66, v225, s[44:45]
	v_cmp_gt_i32_e64 s[44:45], v67, v154
	v_mul_f32_e32 v66, 0x3e38aa3b, v71
	s_and_b64 s[44:45], vcc, s[44:45]
	v_add_u32_e32 v67, 0xffffffaa, v197
	v_cndmask_b32_e64 v88, v66, v225, s[44:45]
	v_cmp_gt_i32_e64 s[44:45], v67, v154
	v_mul_f32_e32 v66, 0x3e38aa3b, v72
	s_and_b64 s[44:45], vcc, s[44:45]
	v_add_u32_e32 v67, 0xffffffab, v197
	v_cndmask_b32_e64 v91, v66, v225, s[44:45]
	v_cmp_gt_i32_e64 s[44:45], v67, v154
	v_mul_f32_e32 v66, 0x3e38aa3b, v73
	s_and_b64 s[44:45], vcc, s[44:45]
	v_add_u32_e32 v67, 0xffffffb0, v197
	v_cndmask_b32_e64 v84, v66, v225, s[44:45]
	v_cmp_gt_i32_e64 s[44:45], v67, v154
	v_mul_f32_e32 v66, 0x3e38aa3b, v74
	s_and_b64 s[44:45], vcc, s[44:45]
	v_add_u32_e32 v67, 0xffffffb1, v197
	v_cndmask_b32_e64 v73, v66, v225, s[44:45]
	v_cmp_gt_i32_e64 s[44:45], v67, v154
	v_mul_f32_e32 v66, 0x3e38aa3b, v75
	s_and_b64 s[44:45], vcc, s[44:45]
	v_add_u32_e32 v67, 0xffffffb2, v197
	v_cndmask_b32_e64 v68, v66, v225, s[44:45]
	v_cmp_gt_i32_e64 s[44:45], v67, v154
	v_mul_f32_e32 v66, 0x3e38aa3b, v76
	s_and_b64 s[44:45], vcc, s[44:45]
	v_add_u32_e32 v67, 0xffffffb3, v197
	v_cndmask_b32_e64 v70, v66, v225, s[44:45]
	v_cmp_gt_i32_e64 s[44:45], v67, v154
	v_mul_f32_e32 v66, 0x3e38aa3b, v77
	s_and_b64 s[44:45], vcc, s[44:45]
	v_add_u32_e32 v67, 0xffffffb8, v197
	v_cndmask_b32_e64 v72, v66, v225, s[44:45]
	v_cmp_gt_i32_e64 s[44:45], v67, v154
	v_mul_f32_e32 v66, 0x3e38aa3b, v78
	s_and_b64 s[44:45], vcc, s[44:45]
	v_add_u32_e32 v69, 0xffffffb9, v197
	v_cndmask_b32_e64 v67, v66, v225, s[44:45]
	v_cmp_gt_i32_e64 s[44:45], v69, v154
	v_mul_f32_e32 v66, 0x3e38aa3b, v79
	s_and_b64 s[44:45], vcc, s[44:45]
	v_add_u32_e32 v71, 0xffffffba, v197
	v_cndmask_b32_e64 v69, v66, v225, s[44:45]
	v_cmp_gt_i32_e64 s[44:45], v71, v154
	v_mul_f32_e32 v66, 0x3e38aa3b, v80
	s_and_b64 s[44:45], vcc, s[44:45]
	v_add_u32_e32 v74, 0xffffffbb, v197
	v_cndmask_b32_e64 v71, v66, v225, s[44:45]
	v_cmp_gt_i32_e64 s[44:45], v74, v154

; DI int crow(int i, int hh) { return (i & 3) + 8 * (i >> 2) + 4 * hh; }
; DI f32x16 mfma(bf16x8 a, bf16x8 b, f32x16 c) { return __builtin_amdgcn_mfma_f32_32x32x16_bf16(a, b, c, 0, 0, 0); }
; DI f32x16 zero16() { f32x16 z; for (int i = 0; i < 16; ++i) z[i] = 0.f; return z; }
; DI void phase_da_attn(const Params& p, int j, char* lds) {
;     ...
;     auto gload = [&](int kt) {
; #pragma unroll
;       for (int i = 0; i < 2; ++i) {
;         int idx = tid + i * NT;
;         { int row = idx >> 4, ch = idx & 15; rk[i] = *(const u32x4*)(K + (tokb + kt * 64 + row) * D_ + h * 128 + ch * 8); }
;         { int row = idx >> 3, ch = idx & 7; rv[i] = *(const u32x4*)(Vt + ((size_t)(b * 8 + h) * 128 + row) * S_ + kt * 64 + ch * 8); }
;       }
;     };
;     auto lwrite = [&](int buf) {
;       char* kt_w = lds + buf * KVB; char* vt_w = kt_w + 16384;
; #pragma unroll
;       for (int i = 0; i < 2; ++i) {
;         int idx = tid + i * NT;
;         { int row = idx >> 4, ch = idx & 15; *(u32x4*)(kt_w + row * 256 + ((ch ^ (row & 15)) << 4)) = rk[i]; }
;         { int row = idx >> 3, ch = idx & 7; char* d = vt_w + row * 136 + ch * 16; u32x2 a = {rv[i].x, rv[i].y}, bq = {rv[i].z, rv[i].w}; *(u32x2*)d = a; *(u32x2*)(d + 8) = bq; }
;       }
;     };
;     ...
;     for (int kt = 0; kt < nkt; ++kt) {
;       if (kt + 1 < nkt) lwrite((kt + 1) & 1);
;       if (kt + 2 < nkt) gload(kt + 2);
;       const char* kt_l = lds + (kt & 1) * KVB; const char* vt_l = kt_l + 16384;
;       if (kt * 64 <= q0 + 31) {
;         f32x16 st[2];
; #pragma unroll
;         for (int mt = 0; mt < 2; ++mt) {
;           st[mt] = zero16();
;           const int row = mt * 32 + l31;
; #pragma unroll
;           for (int kk = 0; kk < 4; ++kk) {
;             int ch = c * 8 + kk * 2 + hh;
;             bf16x8 a = *(const bf16x8*)(kt_l + row * 256 + ((ch ^ (row & 15)) << 4));
;             st[mt] = mfma(a, qf[kk], st[mt]);
;           }
;         }
;         const bool diag = kt * 64 + 63 > q0;
; #pragma unroll
;         for (int mt = 0; mt < 2; ++mt)
; #pragma unroll
;           for (int i = 0; i < 16; ++i) {
;             float s = st[mt][i] * sc;
;             if (diag) { int key = kt * 64 + mt * 32 + crow(i, hh); if (key > myq) s = -1e30f; }
;             st[mt][i] = s;
;           }
.Lda_fast:
	v_add_u32_e32 v155, v70, v183
	v_add_u32_e32 v192, v70, v184
	v_add_u32_e32 v193, v70, v185
	ds_read_b128 v[226:229], v71
	ds_read_b128 v[230:233], v155
	ds_read_b128 v[234:237], v192
	ds_read_b128 v[238:241], v193
	ds_read_b128 v[242:245], v71 offset:8192
	ds_read_b128 v[246:249], v155 offset:8192
	ds_read_b128 v[188:191], v192 offset:8192
	ds_read_b128 v[194:197], v193 offset:8192
	s_waitcnt lgkmcnt(7)
	v_mfma_f32_32x32x16_bf16 v[82:97], v[226:229], v[110:113], 0
	s_waitcnt lgkmcnt(6)
	v_mfma_f32_32x32x16_bf16 v[82:97], v[230:233], v[106:109], v[82:97]
	s_waitcnt lgkmcnt(5)
	v_mfma_f32_32x32x16_bf16 v[82:97], v[234:237], v[102:105], v[82:97]
	s_waitcnt lgkmcnt(4)
	v_mfma_f32_32x32x16_bf16 v[82:97], v[238:241], v[98:101], v[82:97]
	s_waitcnt lgkmcnt(3)
	v_mfma_f32_32x32x16_bf16 v[66:81], v[242:245], v[110:113], 0
	s_waitcnt lgkmcnt(2)
	v_mfma_f32_32x32x16_bf16 v[66:81], v[246:249], v[106:109], v[66:81]
	s_waitcnt lgkmcnt(1)
	v_mfma_f32_32x32x16_bf16 v[66:81], v[188:191], v[102:105], v[66:81]
	s_waitcnt lgkmcnt(0)
	v_mfma_f32_32x32x16_bf16 v[66:81], v[194:197], v[98:101], v[66:81]
	s_cmp_eq_u32 s101, 0
	s_cbranch_scc1 .Lda_fast_nostage
	s_bitcmp1_b32 s37, 0
	s_cselect_b32 s36, 0x8400, 0
	v_add3_u32 v226, s36, v164, v170
	s_waitcnt vmcnt(2)
	ds_write_b128 v226, v[118:121]
	v_add_u32_e32 v226, s36, v171
	v_add3_u32 v226, v226, v172, s91
	ds_write2_b64 v226, v[114:115], v[116:117] offset1:1
	v_add3_u32 v226, s36, v173, v174
	s_waitcnt vmcnt(1)
	ds_write_b128 v226, v[122:125]
	v_add_u32_e32 v226, s36, v175
	v_add3_u32 v226, v226, v172, s91
	s_waitcnt vmcnt(0)
	ds_write2_b64 v226, v[126:127], v[128:129] offset1:1
	s_cmp_ge_u32 s44, s2
	s_cbranch_scc1 .Lda_fast_nostage
	v_mov_b32_e32 v228, s6
	v_mov_b32_e32 v229, 0
	v_lshl_add_u64 v[230:231], v[156:157], 0, v[228:229]
	v_lshlrev_b64 v[230:231], 11, v[230:231]
	v_lshl_add_u64 v[230:231], v[168:169], 0, v[230:231]
	global_load_dwordx4 v[118:121], v[230:231], off
	v_lshlrev_b64 v[232:233], 1, v[228:229]
	v_lshl_add_u64 v[230:231], v[158:159], 0, v[232:233]
	global_load_dwordx4 v[114:117], v[230:231], off
	v_lshl_add_u64 v[230:231], v[160:161], 0, v[228:229]
	v_lshlrev_b64 v[230:231], 11, v[230:231]
	v_lshl_add_u64 v[230:231], v[168:169], 0, v[230:231]
	global_load_dwordx4 v[122:125], v[230:231], off
	v_lshl_add_u64 v[230:231], v[166:167], 0, v[232:233]
	global_load_dwordx4 v[126:129], v[230:231], off
.Lda_fast_nostage:
	s_nop 3
	v_mul_f32_e32 v82, 0x3e38aa3b, v82
	v_mul_f32_e32 v83, 0x3e38aa3b, v83
	v_mul_f32_e32 v155, 0x3e38aa3b, v84
	v_mul_f32_e32 v188, 0x3e38aa3b, v85
	v_mul_f32_e32 v193, 0x3e38aa3b, v86
	v_mul_f32_e32 v194, 0x3e38aa3b, v87
	v_mul_f32_e32 v195, 0x3e38aa3b, v88
	v_mul_f32_e32 v196, 0x3e38aa3b, v89
	v_mul_f32_e32 v191, 0x3e38aa3b, v90
	v_mul_f32_e32 v192, 0x3e38aa3b, v91
	v_mul_f32_e32 v189, 0x3e38aa3b, v92
	v_mul_f32_e32 v190, 0x3e38aa3b, v93
	v_mul_f32_e32 v93, 0x3e38aa3b, v94
	v_mul_f32_e32 v94, 0x3e38aa3b, v95
	v_mul_f32_e32 v95, 0x3e38aa3b, v96
	v_mul_f32_e32 v92, 0x3e38aa3b, v97
	v_mul_f32_e32 v89, 0x3e38aa3b, v66
	v_mul_f32_e32 v85, 0x3e38aa3b, v67
	v_mul_f32_e32 v87, 0x3e38aa3b, v68
	v_mul_f32_e32 v90, 0x3e38aa3b, v69
	v_mul_f32_e32 v86, 0x3e38aa3b, v70
	v_mul_f32_e32 v88, 0x3e38aa3b, v71
	v_mul_f32_e32 v91, 0x3e38aa3b, v72
	v_mul_f32_e32 v84, 0x3e38aa3b, v73
	v_mul_f32_e32 v73, 0x3e38aa3b, v74
	v_mul_f32_e32 v68, 0x3e38aa3b, v75
	v_mul_f32_e32 v70, 0x3e38aa3b, v76
	v_mul_f32_e32 v72, 0x3e38aa3b, v77
	v_mul_f32_e32 v67, 0x3e38aa3b, v78
	v_mul_f32_e32 v69, 0x3e38aa3b, v79
	v_mul_f32_e32 v71, 0x3e38aa3b, v80
	s_mov_b64 vcc, 0
	s_branch .Lda_max
